# v109 plus DPP prefix scan of the log gates in dn_pre step 3 (row shifts and row broadcasts instead of six ds_bpermute round trips)
# baseline (speedup 1.0000x reference)
; __device__ __forceinline__ float bf2f(bfu h) { return __uint_as_float(((unsigned)h) << 16); }
; __device__ __forceinline__ float siluf_(float x) { return x * frcp(1.0f + fexp(-x)); }
; __device__ void dn_pre_item(const Params& p, int L, int idx) {
;     ...
;     _Pragma("unroll") for (int mat = 0; mat < 3; ++mat) {
;       float* dst = (mat == 0) ? qs : (mat == 1 ? ks : vs);
;       float xm3 = head0 ? 0.f : bf2f(xr[mat][0]), xm2 = head0 ? 0.f : bf2f(xr[mat][1]), xm1 = head0 ? 0.f : bf2f(xr[mat][2]);
;       _Pragma("unroll") for (int r = 0; r < 16; ++r) {
;         const float x0 = bf2f(xr[mat][3 + r]);
;         const float y = cwv[mat][0] * xm3 + cwv[mat][1] * xm2 + cwv[mat][2] * xm1 + cwv[mat][3] * x0;
;         dst[(r0 + r) * 132 + c] = siluf_(y);
;         xm3 = xm2; xm2 = xm1; xm1 = x0;
;       }
;     }
.LBB0_374:
	s_or_b64 exec, exec, s[0:1]
	s_waitcnt vmcnt(62)
	v_lshlrev_b32_e32 v5, 16, v95
	v_cndmask_b32_e64 v16, v5, 0, vcc
	v_lshlrev_b32_e32 v5, 16, v97
	v_cndmask_b32_e64 v22, v5, 0, vcc
	v_mul_f32_e32 v26, v48, v22
	s_waitcnt vmcnt(61)
	v_lshlrev_b32_e32 v23, 16, v99
	v_fmac_f32_e32 v26, v46, v16
	s_waitcnt vmcnt(60)
	v_lshlrev_b32_e32 v25, 16, v98
	v_fmac_f32_e32 v26, v49, v23
	v_mul_f32_e32 v17, v46, v52
	v_fmac_f32_e32 v26, v50, v25
	v_fmac_f32_e32 v17, v48, v16
	v_mul_f32_e32 v16, 0xbfb8aa3b, v26
	v_exp_f32_e32 v16, v16
	v_fmac_f32_e32 v17, v49, v22
	v_mul_f32_e32 v28, v48, v23
	v_mul_f32_e32 v30, v48, v25
	v_add_f32_e32 v16, 1.0, v16
	v_rcp_f32_e32 v16, v16
	v_fmac_f32_e32 v17, v50, v23
	v_fmac_f32_e32 v28, v46, v22
	v_fmac_f32_e32 v30, v46, v23
	v_mul_f32_e32 v16, v26, v16
	s_waitcnt vmcnt(59)
	v_lshlrev_b32_e32 v26, 16, v96
	v_mul_f32_e32 v24, 0xbfb8aa3b, v17
	v_fmac_f32_e32 v28, v49, v25
	s_waitcnt vmcnt(58)
	v_lshlrev_b32_e32 v29, 16, v94
	v_fmac_f32_e32 v30, v49, v26
	v_exp_f32_e32 v24, v24
	v_fmac_f32_e32 v28, v50, v26
	v_fmac_f32_e32 v30, v50, v29
	v_mul_f32_e32 v22, 0xbfb8aa3b, v28
	v_mul_f32_e32 v23, 0xbfb8aa3b, v30
	v_exp_f32_e32 v22, v22
	v_exp_f32_e32 v23, v23
	v_mul_f32_e32 v33, v48, v26
	v_fmac_f32_e32 v33, v46, v25
	v_add_f32_e32 v24, 1.0, v24
	s_waitcnt vmcnt(57)
	v_lshlrev_b32_e32 v32, 16, v92
	v_fmac_f32_e32 v33, v49, v29
	v_rcp_f32_e32 v24, v24
	v_fmac_f32_e32 v33, v50, v32
	v_add_f32_e32 v22, 1.0, v22
	v_add_f32_e32 v23, 1.0, v23
	v_mul_f32_e32 v25, 0xbfb8aa3b, v33
	v_add_u32_e32 v20, 0, v51
	v_lshlrev_b32_e32 v5, 2, v60
	s_movk_i32 s0, 0x210
	v_rcp_f32_e32 v22, v22
	v_rcp_f32_e32 v23, v23
	v_exp_f32_e32 v25, v25
	v_add_u32_e32 v27, v20, v5
	v_mul_lo_u32 v2, v2, s0
	v_mul_f32_e32 v24, v17, v24
	v_add_u32_e32 v17, v27, v2
	v_add_u32_e32 v31, 0x4400, v17
	ds_write2_b32 v31, v24, v16 offset1:132
	v_mul_f32_e32 v16, v28, v22
	v_mul_f32_e32 v22, v30, v23
	v_add_f32_e32 v23, 1.0, v25
	v_mul_f32_e32 v25, v48, v29
	v_fmac_f32_e32 v25, v46, v26
	s_waitcnt vmcnt(56)
	v_lshlrev_b32_e32 v24, 16, v89
	v_fmac_f32_e32 v25, v49, v32
	v_fmac_f32_e32 v25, v50, v24
	v_mul_f32_e32 v26, 0xbfb8aa3b, v25
	v_exp_f32_e32 v26, v26
	v_rcp_f32_e32 v23, v23
	v_add_u32_e32 v28, 0x4800, v17
	ds_write2_b32 v28, v16, v22 offset0:8 offset1:140
	v_add_f32_e32 v22, 1.0, v26
	v_mul_f32_e32 v26, v48, v32
	v_fmac_f32_e32 v26, v46, v29
	v_mul_f32_e32 v16, v33, v23
	s_waitcnt vmcnt(55)
	v_lshlrev_b32_e32 v23, 16, v85
	v_fmac_f32_e32 v26, v49, v24
	v_fmac_f32_e32 v26, v50, v23
	v_mul_f32_e32 v28, 0xbfb8aa3b, v26
	v_mul_f32_e32 v30, v48, v24
	v_rcp_f32_e32 v22, v22
	v_exp_f32_e32 v28, v28
	v_fmac_f32_e32 v30, v46, v32
	s_waitcnt vmcnt(54)
	v_lshlrev_b32_e32 v29, 16, v81
	v_fmac_f32_e32 v30, v49, v23
	v_fmac_f32_e32 v30, v50, v29
	v_mul_f32_e32 v31, 0xbfb8aa3b, v30
	v_exp_f32_e32 v31, v31
	v_mul_f32_e32 v22, v25, v22
	v_add_f32_e32 v25, 1.0, v28
	v_rcp_f32_e32 v25, v25
	v_add_f32_e32 v28, 1.0, v31
	v_add_u32_e32 v31, 0x4c00, v17
	ds_write2_b32 v31, v16, v22 offset0:16 offset1:148
	v_mul_f32_e32 v16, v26, v25
	v_mul_f32_e32 v26, v48, v23
	v_fmac_f32_e32 v26, v46, v24
	v_rcp_f32_e32 v28, v28
	s_waitcnt vmcnt(53)
	v_lshlrev_b32_e32 v25, 16, v88
	v_fmac_f32_e32 v26, v49, v29
	v_fmac_f32_e32 v26, v50, v25
	v_mul_f32_e32 v24, 0xbfb8aa3b, v26
	v_exp_f32_e32 v24, v24
	v_mul_f32_e32 v22, v30, v28
	v_mul_f32_e32 v30, v48, v29
	v_fmac_f32_e32 v30, v46, v23
	s_waitcnt vmcnt(52)
	v_lshlrev_b32_e32 v28, 16, v86
	v_fmac_f32_e32 v30, v49, v25
	v_fmac_f32_e32 v30, v50, v28
	v_add_f32_e32 v24, 1.0, v24
	v_mul_f32_e32 v23, 0xbfb8aa3b, v30
	v_rcp_f32_e32 v24, v24
	v_exp_f32_e32 v23, v23
	v_mul_f32_e32 v33, v48, v25
	v_fmac_f32_e32 v33, v46, v29
	v_add_u32_e32 v31, 0x5000, v17
	s_waitcnt vmcnt(51)
	v_lshlrev_b32_e32 v32, 16, v78
	v_fmac_f32_e32 v33, v49, v28
	v_fmac_f32_e32 v33, v50, v32
	ds_write2_b32 v31, v16, v22 offset0:24 offset1:156
	v_mul_f32_e32 v16, v26, v24
	v_mul_f32_e32 v26, v48, v28
	v_add_f32_e32 v23, 1.0, v23
	v_mul_f32_e32 v29, 0xbfb8aa3b, v33
	v_fmac_f32_e32 v26, v46, v25
	v_rcp_f32_e32 v23, v23
	v_exp_f32_e32 v29, v29
	s_waitcnt vmcnt(50)
	v_lshlrev_b32_e32 v24, 16, v76
	v_fmac_f32_e32 v26, v49, v32
	v_fmac_f32_e32 v26, v50, v24
	v_mul_f32_e32 v25, 0xbfb8aa3b, v26
	v_exp_f32_e32 v25, v25
	v_mul_f32_e32 v22, v30, v23
	v_add_f32_e32 v23, 1.0, v29
	v_rcp_f32_e32 v23, v23
	v_add_u32_e32 v29, 0x5400, v17
	ds_write2_b32 v29, v16, v22 offset0:32 offset1:164
	v_add_f32_e32 v22, 1.0, v25
	v_mul_f32_e32 v25, v48, v32
	v_fmac_f32_e32 v25, v46, v28
	v_mul_f32_e32 v16, v33, v23
	s_waitcnt vmcnt(49)
	v_lshlrev_b32_e32 v23, 16, v73
	v_fmac_f32_e32 v25, v49, v24
	v_fmac_f32_e32 v25, v50, v23
	v_mul_f32_e32 v28, 0xbfb8aa3b, v25
	v_mul_f32_e32 v30, v48, v24
	v_rcp_f32_e32 v22, v22
	v_exp_f32_e32 v28, v28
	v_fmac_f32_e32 v30, v46, v32
	s_waitcnt vmcnt(48)
	v_lshlrev_b32_e32 v29, 16, v72
	v_fmac_f32_e32 v30, v49, v23
	v_fmac_f32_e32 v30, v50, v29
	v_mul_f32_e32 v31, 0xbfb8aa3b, v30
	v_exp_f32_e32 v31, v31
	v_mul_f32_e32 v22, v26, v22
	v_add_f32_e32 v26, 1.0, v28
	v_rcp_f32_e32 v26, v26
	v_add_f32_e32 v28, 1.0, v31
	v_add_u32_e32 v31, 0x5800, v17
	v_rcp_f32_e32 v28, v28
	ds_write2_b32 v31, v16, v22 offset0:40 offset1:172
	v_mul_f32_e32 v16, v25, v26
	v_mul_f32_e32 v26, v48, v23
	v_fmac_f32_e32 v26, v46, v24
	v_fmac_f32_e32 v26, v49, v29
	v_mul_f32_e32 v29, v48, v29
	s_waitcnt vmcnt(47)
	v_lshlrev_b32_e32 v25, 16, v70
	v_fmac_f32_e32 v29, v46, v23
	v_mul_f32_e32 v22, v30, v28
	v_fmac_f32_e32 v26, v50, v25
	s_waitcnt vmcnt(46)
; __device__ __forceinline__ float bf2f(bfu h) { return __uint_as_float(((unsigned)h) << 16); }
; __device__ __forceinline__ float siluf_(float x) { return x * frcp(1.0f + fexp(-x)); }
; __device__ void dn_pre_item(const Params& p, int L, int idx) {
;     ...
;     _Pragma("unroll") for (int mat = 0; mat < 3; ++mat) {
;       float* dst = (mat == 0) ? qs : (mat == 1 ? ks : vs);
;       float xm3 = head0 ? 0.f : bf2f(xr[mat][0]), xm2 = head0 ? 0.f : bf2f(xr[mat][1]), xm1 = head0 ? 0.f : bf2f(xr[mat][2]);
;       _Pragma("unroll") for (int r = 0; r < 16; ++r) {
;         const float x0 = bf2f(xr[mat][3 + r]);
;         const float y = cwv[mat][0] * xm3 + cwv[mat][1] * xm2 + cwv[mat][2] * xm1 + cwv[mat][3] * x0;
;         dst[(r0 + r) * 132 + c] = siluf_(y);
;         xm3 = xm2; xm2 = xm1; xm1 = x0;
;       }
;     }
	v_lshlrev_b32_e32 v28, 16, v74
	v_fmac_f32_e32 v29, v49, v25
	v_mul_f32_e32 v24, 0xbfb8aa3b, v26
	v_fmac_f32_e32 v29, v50, v28
	v_exp_f32_e32 v24, v24
	v_mul_f32_e32 v23, 0xbfb8aa3b, v29
	v_exp_f32_e32 v23, v23
	v_add_u32_e32 v25, 0x5c00, v17
	v_add_f32_e32 v24, 1.0, v24
	v_rcp_f32_e32 v24, v24
	v_add_f32_e32 v23, 1.0, v23
	v_rcp_f32_e32 v23, v23
	ds_write2_b32 v25, v16, v22 offset0:48 offset1:180
	v_mul_f32_e32 v16, v26, v24
	s_waitcnt vmcnt(39)
	v_lshlrev_b32_e32 v24, 16, v87
	v_mul_f32_e32 v22, v29, v23
	v_lshlrev_b32_e32 v23, 16, v83
	v_cndmask_b32_e64 v24, v24, 0, vcc
	v_cndmask_b32_e64 v23, v23, 0, vcc
	s_waitcnt vmcnt(37)
	v_lshlrev_b32_e32 v25, 16, v90
	v_mul_f32_e32 v28, v45, v24
	v_cndmask_b32_e64 v25, v25, 0, vcc
	v_fmac_f32_e32 v28, v39, v23
	v_lshlrev_b32_e32 v26, 16, v93
	v_fmac_f32_e32 v28, v44, v25
	v_mul_f32_e32 v30, v45, v25
	v_fmac_f32_e32 v28, v47, v26
	v_fmac_f32_e32 v30, v39, v24
	v_mul_f32_e32 v23, 0xbfb8aa3b, v28
	v_lshlrev_b32_e32 v29, 16, v91
	v_fmac_f32_e32 v30, v44, v26
	v_exp_f32_e32 v23, v23
	v_fmac_f32_e32 v30, v47, v29
	v_mul_f32_e32 v24, 0xbfb8aa3b, v30
	v_exp_f32_e32 v24, v24
	v_mul_f32_e32 v32, v45, v26
	v_fmac_f32_e32 v32, v39, v25
	v_add_f32_e32 v23, 1.0, v23
	s_waitcnt vmcnt(36)
	v_lshlrev_b32_e32 v31, 16, v84
	v_fmac_f32_e32 v32, v44, v29
	v_rcp_f32_e32 v23, v23
	v_fmac_f32_e32 v32, v47, v31
	ds_write_b32 v17, v16 offset:24800
	v_or_b32_e32 v16, 15, v43
	v_add_f32_e32 v24, 1.0, v24
	v_mul_f32_e32 v25, 0xbfb8aa3b, v32
	v_mul_lo_u32 v16, v16, s0
	v_rcp_f32_e32 v24, v24
	v_exp_f32_e32 v25, v25
	v_add_u32_e32 v27, v27, v16
	ds_write_b32 v27, v22 offset:17408
	v_mul_f32_e32 v22, v28, v23
	v_mul_f32_e32 v28, v45, v29
	v_fmac_f32_e32 v28, v39, v26
	v_mul_f32_e32 v23, v30, v24
	v_add_f32_e32 v24, 1.0, v25
	s_waitcnt vmcnt(35)
	v_lshlrev_b32_e32 v25, 16, v77
	v_fmac_f32_e32 v28, v44, v31
	v_fmac_f32_e32 v28, v47, v25
	v_mul_f32_e32 v26, 0xbfb8aa3b, v28
	v_exp_f32_e32 v26, v26
	v_rcp_f32_e32 v24, v24
	v_add_u32_e32 v30, 0xc800, v17
	ds_write2_b32 v30, v22, v23 offset1:132
	v_add_f32_e32 v23, 1.0, v26
	v_mul_f32_e32 v26, v45, v31
	v_fmac_f32_e32 v26, v39, v29
	v_mul_f32_e32 v22, v32, v24
	s_waitcnt vmcnt(34)
	v_lshlrev_b32_e32 v24, 16, v80
	v_fmac_f32_e32 v26, v44, v25
	v_fmac_f32_e32 v26, v47, v24
	v_mul_f32_e32 v29, 0xbfb8aa3b, v26
	v_mul_f32_e32 v32, v45, v25
	v_rcp_f32_e32 v23, v23
	v_exp_f32_e32 v29, v29
	v_fmac_f32_e32 v32, v39, v31
	s_waitcnt vmcnt(33)
	v_lshlrev_b32_e32 v30, 16, v75
	v_fmac_f32_e32 v32, v44, v24
	v_fmac_f32_e32 v32, v47, v30
	v_mul_f32_e32 v31, 0xbfb8aa3b, v32
	v_exp_f32_e32 v31, v31
	v_mul_f32_e32 v23, v28, v23
	v_add_f32_e32 v28, 1.0, v29
	v_rcp_f32_e32 v28, v28
	v_add_f32_e32 v29, 1.0, v31
	v_add_u32_e32 v31, 0xcc00, v17
	ds_write2_b32 v31, v22, v23 offset0:8 offset1:140
	v_mul_f32_e32 v22, v26, v28
	v_mul_f32_e32 v28, v45, v24
	v_fmac_f32_e32 v28, v39, v25
	s_waitcnt vmcnt(32)
	v_lshlrev_b32_e32 v26, 16, v71
	v_fmac_f32_e32 v28, v44, v30
	v_fmac_f32_e32 v28, v47, v26
	v_rcp_f32_e32 v29, v29
	v_mul_f32_e32 v25, 0xbfb8aa3b, v28
	v_exp_f32_e32 v25, v25
	v_mul_f32_e32 v31, v45, v30
	v_fmac_f32_e32 v31, v39, v24
	v_mul_f32_e32 v23, v32, v29
	s_waitcnt vmcnt(31)
	v_lshlrev_b32_e32 v29, 16, v69
	v_fmac_f32_e32 v31, v44, v26
	v_fmac_f32_e32 v31, v47, v29
	v_add_f32_e32 v25, 1.0, v25
	v_mul_f32_e32 v24, 0xbfb8aa3b, v31
	v_rcp_f32_e32 v25, v25
	v_exp_f32_e32 v24, v24
	v_mul_f32_e32 v34, v45, v26
	v_fmac_f32_e32 v34, v39, v30
	v_add_u32_e32 v32, 0xd000, v17
	s_waitcnt vmcnt(30)
	v_lshlrev_b32_e32 v33, 16, v68
	v_fmac_f32_e32 v34, v44, v29
	v_fmac_f32_e32 v34, v47, v33
	ds_write2_b32 v32, v22, v23 offset0:16 offset1:148
	v_mul_f32_e32 v22, v28, v25
	v_mul_f32_e32 v28, v45, v29
	v_add_f32_e32 v24, 1.0, v24
	v_mul_f32_e32 v30, 0xbfb8aa3b, v34
	v_fmac_f32_e32 v28, v39, v26
	v_rcp_f32_e32 v24, v24
	v_exp_f32_e32 v30, v30
	s_waitcnt vmcnt(29)
	v_lshlrev_b32_e32 v25, 16, v67
	v_fmac_f32_e32 v28, v44, v33
	v_fmac_f32_e32 v28, v47, v25
	v_mul_f32_e32 v26, 0xbfb8aa3b, v28
	v_exp_f32_e32 v26, v26
	v_mul_f32_e32 v23, v31, v24
	v_add_f32_e32 v24, 1.0, v30
	v_rcp_f32_e32 v24, v24
	v_add_u32_e32 v30, 0xd400, v17
	ds_write2_b32 v30, v22, v23 offset0:24 offset1:156
	v_add_f32_e32 v23, 1.0, v26
	v_mul_f32_e32 v26, v45, v33
	v_fmac_f32_e32 v26, v39, v29
	v_mul_f32_e32 v22, v34, v24
	s_waitcnt vmcnt(28)
	v_lshlrev_b32_e32 v24, 16, v64
	v_fmac_f32_e32 v26, v44, v25
	v_fmac_f32_e32 v26, v47, v24
	v_mul_f32_e32 v29, 0xbfb8aa3b, v26
	v_mul_f32_e32 v31, v45, v25
	v_rcp_f32_e32 v23, v23
	v_exp_f32_e32 v29, v29
	v_fmac_f32_e32 v31, v39, v33
	s_waitcnt vmcnt(27)
	v_lshlrev_b32_e32 v30, 16, v58
	v_fmac_f32_e32 v31, v44, v24
	v_fmac_f32_e32 v31, v47, v30
	v_mul_f32_e32 v32, 0xbfb8aa3b, v31
	v_exp_f32_e32 v32, v32
	v_mul_f32_e32 v23, v28, v23
	v_add_f32_e32 v28, 1.0, v29
	v_rcp_f32_e32 v28, v28
	v_add_f32_e32 v29, 1.0, v32
	v_add_u32_e32 v32, 0xd800, v17
	ds_write2_b32 v32, v22, v23 offset0:32 offset1:164
	v_mul_f32_e32 v22, v26, v28
	v_mul_f32_e32 v28, v45, v24
	v_rcp_f32_e32 v29, v29
	v_fmac_f32_e32 v28, v39, v25
	s_waitcnt vmcnt(26)
	v_lshlrev_b32_e32 v26, 16, v62
	v_fmac_f32_e32 v28, v44, v30
	v_fmac_f32_e32 v28, v47, v26
	v_mul_f32_e32 v25, 0xbfb8aa3b, v28
	v_mul_f32_e32 v23, v31, v29
	v_exp_f32_e32 v25, v25
	v_mul_f32_e32 v31, v45, v30
	v_fmac_f32_e32 v31, v39, v24
	s_waitcnt vmcnt(25)
	v_lshlrev_b32_e32 v29, 16, v57
	v_fmac_f32_e32 v31, v44, v26
	v_fmac_f32_e32 v31, v47, v29
	v_mul_f32_e32 v24, 0xbfb8aa3b, v31
	v_add_f32_e32 v25, 1.0, v25
	v_exp_f32_e32 v24, v24
	v_rcp_f32_e32 v25, v25
	v_mul_f32_e32 v34, v45, v26
	v_fmac_f32_e32 v34, v39, v30
	s_waitcnt vmcnt(24)
; __device__ __forceinline__ float bf2f(bfu h) { return __uint_as_float(((unsigned)h) << 16); }
; __device__ __forceinline__ float siluf_(float x) { return x * frcp(1.0f + fexp(-x)); }
; __device__ void dn_pre_item(const Params& p, int L, int idx) {
;     ...
;     _Pragma("unroll") for (int mat = 0; mat < 3; ++mat) {
;       float* dst = (mat == 0) ? qs : (mat == 1 ? ks : vs);
;       float xm3 = head0 ? 0.f : bf2f(xr[mat][0]), xm2 = head0 ? 0.f : bf2f(xr[mat][1]), xm1 = head0 ? 0.f : bf2f(xr[mat][2]);
;       _Pragma("unroll") for (int r = 0; r < 16; ++r) {
;         const float x0 = bf2f(xr[mat][3 + r]);
;         const float y = cwv[mat][0] * xm3 + cwv[mat][1] * xm2 + cwv[mat][2] * xm1 + cwv[mat][3] * x0;
;         dst[(r0 + r) * 132 + c] = siluf_(y);
;         xm3 = xm2; xm2 = xm1; xm1 = x0;
;       }
;     }
;   }
;   __syncthreads();
;   { const int rowid = tid >> 2, part = tid & 3;
;     const bool isq = rowid < 64; const int rr = isq ? rowid : rowid - 64;
;     float* base = (isq ? qs : ks) + rr * 132;
	v_lshlrev_b32_e32 v33, 16, v55
	v_fmac_f32_e32 v34, v44, v29
	v_add_u32_e32 v32, 0xdc00, v17
	v_fmac_f32_e32 v34, v47, v33
	v_add_f32_e32 v24, 1.0, v24
	v_mul_f32_e32 v30, 0xbfb8aa3b, v34
	ds_write2_b32 v32, v22, v23 offset0:40 offset1:172
	v_mul_f32_e32 v22, v28, v25
	v_mul_f32_e32 v28, v45, v29
	v_rcp_f32_e32 v24, v24
	v_exp_f32_e32 v30, v30
	v_fmac_f32_e32 v28, v39, v26
	s_waitcnt vmcnt(23)
	v_lshlrev_b32_e32 v25, 16, v53
	v_fmac_f32_e32 v28, v44, v33
	v_fmac_f32_e32 v28, v47, v25
	v_mul_f32_e32 v25, 0xbfb8aa3b, v28
	v_mul_f32_e32 v23, v31, v24
	v_add_f32_e32 v24, 1.0, v30
	v_exp_f32_e32 v25, v25
	v_rcp_f32_e32 v24, v24
	v_add_u32_e32 v26, 0xe000, v17
	ds_write2_b32 v26, v22, v23 offset0:48 offset1:180
	v_add_f32_e32 v23, 1.0, v25
	s_waitcnt vmcnt(6)
	v_lshlrev_b32_e32 v25, 16, v63
	v_mul_f32_e32 v22, v34, v24
	v_lshlrev_b32_e32 v24, 16, v61
	v_cndmask_b32_e64 v25, v25, 0, vcc
	v_cndmask_b32_e64 v24, v24, 0, vcc
	s_waitcnt vmcnt(4)
	v_lshlrev_b32_e32 v26, 16, v65
	v_mul_f32_e32 v30, v36, v25
	v_cndmask_b32_e64 v26, v26, 0, vcc
	v_fmac_f32_e32 v30, v3, v24
	s_waitcnt vmcnt(2)
	v_lshlrev_b32_e32 v29, 16, v66
	v_fmac_f32_e32 v30, v37, v26
	v_fmac_f32_e32 v30, v38, v29
	v_rcp_f32_e32 v23, v23
	v_mul_f32_e32 v24, 0xbfb8aa3b, v30
	v_exp_f32_e32 v24, v24
	ds_write_b32 v17, v22 offset:58592
	v_mul_f32_e32 v17, v28, v23
	ds_write_b32 v27, v17 offset:51200
	v_add_f32_e32 v17, 1.0, v24
	v_mul_f32_e32 v23, v36, v26
	v_rcp_f32_e32 v17, v17
	v_fmac_f32_e32 v23, v3, v25
	v_lshlrev_b32_e32 v22, 16, v59
	v_fmac_f32_e32 v23, v37, v29
	v_fmac_f32_e32 v23, v38, v22
	v_mul_f32_e32 v24, 0xbfb8aa3b, v23
	v_exp_f32_e32 v24, v24
	v_mul_f32_e32 v17, v30, v17
	v_mul_f32_e32 v27, v36, v29
	v_mul_f32_e32 v30, v36, v22
	v_lshlrev_b32_e32 v25, 16, v56
	v_fmac_f32_e32 v27, v3, v26
	v_fmac_f32_e32 v30, v3, v29
	v_fmac_f32_e32 v27, v37, v22
	v_lshlrev_b32_e32 v28, 16, v54
	v_fmac_f32_e32 v30, v37, v25
	v_fmac_f32_e32 v27, v38, v25
	v_fmac_f32_e32 v30, v38, v28
	v_add_f32_e32 v24, 1.0, v24
	v_mul_f32_e32 v26, 0xbfb8aa3b, v27
	v_mul_f32_e32 v29, 0xbfb8aa3b, v30
	v_rcp_f32_e32 v24, v24
	v_exp_f32_e32 v26, v26
	v_exp_f32_e32 v29, v29
	v_add_u32_e32 v21, 0x14c00, v20
	v_mul_f32_e32 v23, v23, v24
	v_add_f32_e32 v24, 1.0, v26
	v_add_f32_e32 v26, 1.0, v29
	v_mul_f32_e32 v29, v36, v25
	v_rcp_f32_e32 v24, v24
	v_fmac_f32_e32 v29, v3, v22
	v_lshlrev_b32_e32 v19, 16, v19
	v_fmac_f32_e32 v29, v37, v28
	v_add_u32_e32 v5, v21, v5
	v_fmac_f32_e32 v29, v38, v19
	v_add_u32_e32 v2, v5, v2
	v_mul_f32_e32 v22, 0xbfb8aa3b, v29
	v_rcp_f32_e32 v26, v26
	v_exp_f32_e32 v22, v22
	ds_write2_b32 v2, v17, v23 offset1:132
	v_mul_f32_e32 v17, v27, v24
	v_mul_f32_e32 v24, v36, v28
	v_fmac_f32_e32 v24, v3, v25
	v_lshlrev_b32_e32 v18, 16, v18
	v_fmac_f32_e32 v24, v37, v19
	v_fmac_f32_e32 v24, v38, v18
	v_mul_f32_e32 v23, v30, v26
	v_add_f32_e32 v22, 1.0, v22
	v_mul_f32_e32 v25, 0xbfb8aa3b, v24
	v_add_u32_e32 v26, 0x400, v2
	v_rcp_f32_e32 v22, v22
	v_exp_f32_e32 v25, v25
	ds_write2_b32 v26, v17, v23 offset0:8 offset1:140
	v_mul_f32_e32 v23, v36, v19
	v_fmac_f32_e32 v23, v3, v28
	v_lshlrev_b32_e32 v15, 16, v15
	v_fmac_f32_e32 v23, v37, v18
	v_fmac_f32_e32 v23, v38, v15
	v_mul_f32_e32 v17, v29, v22
	v_add_f32_e32 v22, 1.0, v25
	v_mul_f32_e32 v25, 0xbfb8aa3b, v23
	v_rcp_f32_e32 v22, v22
	v_exp_f32_e32 v25, v25
	v_mul_f32_e32 v26, v36, v18
	v_fmac_f32_e32 v26, v3, v19
	v_mul_f32_e32 v22, v24, v22
	v_add_f32_e32 v24, 1.0, v25
	v_add_u32_e32 v25, 0x800, v2
	ds_write2_b32 v25, v17, v22 offset0:16 offset1:148
	v_mul_f32_e32 v22, v36, v15
	v_lshlrev_b32_e32 v14, 16, v14
	v_fmac_f32_e32 v26, v37, v15
	v_fmac_f32_e32 v22, v3, v18
	v_fmac_f32_e32 v26, v38, v14
	v_lshlrev_b32_e32 v13, 16, v13
	v_fmac_f32_e32 v22, v37, v14
	v_mul_f32_e32 v19, 0xbfb8aa3b, v26
	v_fmac_f32_e32 v22, v38, v13
	v_exp_f32_e32 v19, v19
	v_mul_f32_e32 v18, 0xbfb8aa3b, v22
	v_exp_f32_e32 v18, v18
	v_rcp_f32_e32 v24, v24
	v_add_f32_e32 v19, 1.0, v19
	v_rcp_f32_e32 v19, v19
	v_add_f32_e32 v18, 1.0, v18
	v_rcp_f32_e32 v18, v18
	v_mul_f32_e32 v17, v23, v24
	v_mul_f32_e32 v19, v26, v19
	v_lshlrev_b32_e32 v12, 16, v12
	v_mul_f32_e32 v23, v36, v14
	v_add_u32_e32 v24, 0xc00, v2
	v_fmac_f32_e32 v23, v3, v15
	v_mul_f32_e32 v25, v36, v13
	ds_write2_b32 v24, v17, v19 offset0:24 offset1:156
	v_mul_f32_e32 v17, v22, v18
	v_mul_f32_e32 v18, v36, v12
	v_fmac_f32_e32 v23, v37, v13
	v_lshlrev_b32_e32 v11, 16, v11
	v_fmac_f32_e32 v25, v3, v14
	v_fmac_f32_e32 v18, v3, v13
	v_fmac_f32_e32 v23, v38, v12
	v_fmac_f32_e32 v25, v37, v12
	v_lshlrev_b32_e32 v9, 16, v9
	v_fmac_f32_e32 v18, v37, v11
	v_mul_f32_e32 v15, 0xbfb8aa3b, v23
	v_fmac_f32_e32 v25, v38, v11
	v_fmac_f32_e32 v18, v38, v9
	v_exp_f32_e32 v15, v15
	v_mul_f32_e32 v14, 0xbfb8aa3b, v25
	v_mul_f32_e32 v13, 0xbfb8aa3b, v18
	v_exp_f32_e32 v14, v14
	v_exp_f32_e32 v13, v13
	v_add_f32_e32 v15, 1.0, v15
	v_rcp_f32_e32 v15, v15
	v_add_f32_e32 v14, 1.0, v14
	v_add_f32_e32 v13, 1.0, v13
	v_rcp_f32_e32 v14, v14
	v_rcp_f32_e32 v13, v13
	v_mul_f32_e32 v15, v23, v15
	v_add_u32_e32 v19, 0x1000, v2
	ds_write2_b32 v19, v17, v15 offset0:32 offset1:164
	v_mul_f32_e32 v14, v25, v14
	v_lshlrev_b32_e32 v10, 16, v10
	v_mul_f32_e32 v17, v36, v9
	v_mul_f32_e32 v13, v18, v13
	v_add_u32_e32 v18, 0x1400, v2
	v_mul_f32_e32 v15, v36, v11
	v_fmac_f32_e32 v17, v3, v11
	ds_write2_b32 v18, v14, v13 offset0:40 offset1:172
	v_mul_f32_e32 v13, v36, v10
	v_fmac_f32_e32 v15, v3, v12
	v_lshlrev_b32_e32 v8, 16, v8
	v_fmac_f32_e32 v17, v37, v10
	v_fmac_f32_e32 v13, v3, v9
	v_fmac_f32_e32 v15, v37, v9
	v_fmac_f32_e32 v17, v38, v8
	v_fmac_f32_e32 v13, v37, v8
	v_mul_f32_e32 v8, v36, v8
	v_fmac_f32_e32 v15, v38, v10
	s_waitcnt vmcnt(1)
	v_lshlrev_b32_e32 v6, 16, v6
	v_fmac_f32_e32 v8, v3, v10
	v_mul_f32_e32 v12, 0xbfb8aa3b, v15
	v_mul_f32_e32 v11, 0xbfb8aa3b, v17
	v_fmac_f32_e32 v13, v38, v6
	s_waitcnt vmcnt(0)
	v_lshlrev_b32_e32 v7, 16, v7
	v_fmac_f32_e32 v8, v37, v6
	v_exp_f32_e32 v12, v12
	v_exp_f32_e32 v11, v11
	v_mul_f32_e32 v9, 0xbfb8aa3b, v13
	v_fmac_f32_e32 v8, v38, v7
	v_exp_f32_e32 v9, v9
	v_mul_f32_e32 v3, 0xbfb8aa3b, v8
	v_exp_f32_e32 v3, v3
	v_add_f32_e32 v12, 1.0, v12
	v_add_f32_e32 v11, 1.0, v11
	v_rcp_f32_e32 v12, v12
	v_rcp_f32_e32 v11, v11
	v_add_f32_e32 v7, 1.0, v9
	v_rcp_f32_e32 v7, v7
	v_add_f32_e32 v3, 1.0, v3
	v_rcp_f32_e32 v3, v3
	v_mul_f32_e32 v12, v15, v12
	v_mul_f32_e32 v11, v17, v11
	v_add_u32_e32 v6, 0x1800, v2
	ds_write2_b32 v6, v12, v11 offset0:48 offset1:180
	v_mul_f32_e32 v6, v13, v7
	ds_write_b32 v2, v6 offset:7392
	v_mul_f32_e32 v2, v8, v3
	v_add_u32_e32 v3, v5, v16
	ds_write_b32 v3, v2
	v_ashrrev_i32_e32 v2, 2, v40
	v_subrev_u32_e32 v3, 64, v2
	v_cmp_gt_i32_e32 vcc, 64, v2
	v_add_u32_e32 v0, 0x4400, v20
	v_add_u32_e32 v4, 0xc800, v20
	v_and_b32_e32 v23, 3, v40
	v_cndmask_b32_e32 v35, v3, v2, vcc
	v_cndmask_b32_e32 v0, v4, v0, vcc
	v_mul_lo_u32 v2, v35, s0
	v_lshlrev_b32_e32 v3, 2, v23
	v_add3_u32 v43, v0, v2, v3
	s_waitcnt lgkmcnt(0)
	s_barrier
; __device__ __forceinline__ float frsq(float x) { return __builtin_amdgcn_rsqf(x); }
; #define SHX(v, m) shx_((v), (m), lane)
; __device__ void dn_pre_item(const Params& p, int L, int idx) {
;     ...
;   { const int rowid = tid >> 2, part = tid & 3;
;     const bool isq = rowid < 64; const int rr = isq ? rowid : rowid - 64;
;     float* base = (isq ? qs : ks) + rr * 132;
;     bfu* bb = (isq ? qb : kb) + rr * 136;
;     float ss = 0.f;
;     for (int i = 0; i < 32; ++i) { float v = base[part + 4 * i]; ss += v * v; }
;     ss += SHX(ss, 1); ss += SHX(ss, 2);
;     float sc = frsq(ss + 1e-6f) * (isq ? 0.08838834764831845f : 1.0f);
	ds_read2_b32 v[2:3], v43 offset1:4
	ds_read2_b32 v[4:5], v43 offset0:4 offset1:8
	ds_read2_b32 v[6:7], v43 offset0:8 offset1:12
	ds_read2_b32 v[8:9], v43 offset0:12 offset1:16
	ds_read2_b32 v[10:11], v43 offset0:16 offset1:20
	ds_read2_b32 v[12:13], v43 offset0:20 offset1:24
	ds_read2_b32 v[14:15], v43 offset0:24 offset1:28
	ds_read2_b32 v[16:17], v43 offset0:28 offset1:32
	ds_read2_b32 v[18:19], v43 offset0:32 offset1:36
	ds_read2_b32 v[24:25], v43 offset0:36 offset1:40
	ds_read2_b32 v[26:27], v43 offset0:40 offset1:44
	ds_read2_b32 v[28:29], v43 offset0:44 offset1:48
	ds_read2_b32 v[30:31], v43 offset0:48 offset1:52
	ds_read2_b32 v[32:33], v43 offset0:52 offset1:56
	ds_read2_b32 v[36:37], v43 offset0:56 offset1:60
	ds_read2_b32 v[38:39], v43 offset0:60 offset1:64
	s_waitcnt lgkmcnt(14)
	v_mul_f32_e32 v0, v3, v3
	v_fmac_f32_e32 v0, v2, v2
	v_fmac_f32_e32 v0, v5, v5
	s_waitcnt lgkmcnt(13)
	v_fmac_f32_e32 v0, v7, v7
	s_waitcnt lgkmcnt(12)
	v_fmac_f32_e32 v0, v9, v9
	s_waitcnt lgkmcnt(11)
	v_fmac_f32_e32 v0, v11, v11
	s_waitcnt lgkmcnt(10)
	v_fmac_f32_e32 v0, v13, v13
	s_waitcnt lgkmcnt(9)
	v_fmac_f32_e32 v0, v15, v15
	s_waitcnt lgkmcnt(8)
	v_fmac_f32_e32 v0, v17, v17
	s_waitcnt lgkmcnt(7)
	v_fmac_f32_e32 v0, v19, v19
	s_waitcnt lgkmcnt(6)
	v_fmac_f32_e32 v0, v25, v25
	s_waitcnt lgkmcnt(5)
	v_fmac_f32_e32 v0, v27, v27
	s_waitcnt lgkmcnt(4)
	v_fmac_f32_e32 v0, v29, v29
	s_waitcnt lgkmcnt(3)
	v_fmac_f32_e32 v0, v31, v31
	s_waitcnt lgkmcnt(2)
	v_fmac_f32_e32 v0, v33, v33
	s_waitcnt lgkmcnt(1)
	v_fmac_f32_e32 v0, v37, v37
	s_waitcnt lgkmcnt(0)
	v_fmac_f32_e32 v0, v39, v39
	ds_read2_b32 v[44:45], v43 offset0:64 offset1:68
	ds_read2_b32 v[46:47], v43 offset0:68 offset1:72
	ds_read2_b32 v[48:49], v43 offset0:72 offset1:76
	ds_read2_b32 v[50:51], v43 offset0:76 offset1:80
	ds_read2_b32 v[52:53], v43 offset0:80 offset1:84
	s_waitcnt lgkmcnt(4)
	v_fmac_f32_e32 v0, v45, v45
	s_waitcnt lgkmcnt(3)
	v_fmac_f32_e32 v0, v47, v47
	s_waitcnt lgkmcnt(2)
	v_fmac_f32_e32 v0, v49, v49
	s_waitcnt lgkmcnt(1)
	v_fmac_f32_e32 v0, v51, v51
	s_waitcnt lgkmcnt(0)
	v_fmac_f32_e32 v0, v53, v53
	ds_read2_b32 v[54:55], v43 offset0:84 offset1:88
	ds_read2_b32 v[56:57], v43 offset0:88 offset1:92
	ds_read2_b32 v[58:59], v43 offset0:92 offset1:96
	ds_read2_b32 v[60:61], v43 offset0:96 offset1:100
	ds_read2_b32 v[62:63], v43 offset0:100 offset1:104
	s_waitcnt lgkmcnt(4)
	v_fmac_f32_e32 v0, v55, v55
	s_waitcnt lgkmcnt(3)
	v_fmac_f32_e32 v0, v57, v57
	s_waitcnt lgkmcnt(2)
	v_fmac_f32_e32 v0, v59, v59
	s_waitcnt lgkmcnt(1)
	v_fmac_f32_e32 v0, v61, v61
	s_waitcnt lgkmcnt(0)
	v_fmac_f32_e32 v0, v63, v63
	ds_read2_b32 v[64:65], v43 offset0:104 offset1:108
	ds_read2_b32 v[66:67], v43 offset0:108 offset1:112
	ds_read2_b32 v[68:69], v43 offset0:112 offset1:116
	ds_read2_b32 v[70:71], v43 offset0:116 offset1:120
	ds_read2_b32 v[72:73], v43 offset0:120 offset1:124
	s_waitcnt lgkmcnt(4)
	v_fmac_f32_e32 v0, v65, v65
	s_waitcnt lgkmcnt(3)
	v_fmac_f32_e32 v0, v67, v67
	v_and_b32_e32 v22, 63, v40
	s_waitcnt lgkmcnt(2)
	v_fmac_f32_e32 v0, v69, v69
	s_waitcnt lgkmcnt(1)
	v_fmac_f32_e32 v0, v71, v71
	v_lshlrev_b32_e32 v49, 2, v22
	s_waitcnt lgkmcnt(0)
	v_fmac_f32_e32 v0, v73, v73
	v_xor_b32_e32 v3, 4, v49
	ds_bpermute_b32 v3, v3, v0
	v_mov_b32_e32 v9, 0x3db504f3
	v_cndmask_b32_e32 v9, 1.0, v9, vcc
	v_add_u32_e32 v34, 0x1d000, v20
	v_lshlrev_b32_e32 v11, 1, v23
	s_waitcnt lgkmcnt(0)
	v_add_f32_e32 v3, v0, v3
	v_xor_b32_e32 v0, 8, v49
	ds_bpermute_b32 v5, v0, v3
	v_add_u32_e32 v0, 0x21400, v20
	v_cndmask_b32_e32 v7, v34, v0, vcc
	s_waitcnt lgkmcnt(0)
; __device__ __forceinline__ float fexp(float x) { return __builtin_amdgcn_exp2f(x * 1.4426950408889634f); }
; __device__ __forceinline__ float frsq(float x) { return __builtin_amdgcn_rsqf(x); }
; __device__ __forceinline__ float shup_(float v, int o, int lane) { return __builtin_bit_cast(float, __builtin_amdgcn_ds_bpermute((lane - o) << 2, __builtin_bit_cast(int, v))); }
; __device__ void dn_pre_item(const Params& p, int L, int idx) {
;     ...
;     float sc = frsq(ss + 1e-6f) * (isq ? 0.08838834764831845f : 1.0f);
;     for (int i = 0; i < 32; ++i) { float v = base[part + 4 * i] * sc; base[part + 4 * i] = v; bb[part + 4 * i] = f2bf(v); }
;   }
;   if (wid == 0) {
;     float gv = gv_pre;
;     for (int o = 1; o < 64; o <<= 1) { float t = shup_(gv, o, lane); if (lane >= o) gv += t; }
;     gcs[lane] = gv; egc[lane] = fexp(gv);
;     betas[lane] = be_pre;
;   }
	v_add_f32_e32 v3, v3, v5
	v_add_f32_e32 v3, 0x358637bd, v3
	v_rsq_f32_e32 v3, v3
	v_mul_lo_u32 v5, v35, s88
	v_add3_u32 v5, v7, v5, v11
	v_mul_f32_e32 v3, v9, v3
	v_mul_f32_e32 v2, v2, v3
	v_bfe_u32 v9, v2, 16, 1
	v_mul_f32_e32 v4, v4, v3
	v_add3_u32 v9, v2, v9, s72
	ds_write2_b32 v43, v2, v4 offset1:4
	v_bfe_u32 v2, v4, 16, 1
	v_add3_u32 v2, v4, v2, s72
	ds_write_b16_d16_hi v5, v2 offset:8
	v_mul_f32_e32 v2, v3, v6
	v_bfe_u32 v4, v2, 16, 1
	v_add3_u32 v4, v2, v4, s72
	ds_write_b16_d16_hi v5, v4 offset:16
	v_mul_f32_e32 v4, v3, v8
	ds_write2_b32 v43, v2, v4 offset0:8 offset1:12
	v_bfe_u32 v2, v4, 16, 1
	v_add3_u32 v2, v4, v2, s72
	ds_write_b16_d16_hi v5, v2 offset:24
	v_mul_f32_e32 v2, v3, v10
	v_bfe_u32 v4, v2, 16, 1
	v_add3_u32 v4, v2, v4, s72
	ds_write_b16_d16_hi v5, v4 offset:32
	v_mul_f32_e32 v4, v3, v12
	ds_write2_b32 v43, v2, v4 offset0:16 offset1:20
	v_bfe_u32 v2, v4, 16, 1
	v_add3_u32 v2, v4, v2, s72
	ds_write_b16_d16_hi v5, v2 offset:40
	v_mul_f32_e32 v2, v3, v14
	v_bfe_u32 v4, v2, 16, 1
	v_add3_u32 v4, v2, v4, s72
	ds_write_b16_d16_hi v5, v4 offset:48
	v_mul_f32_e32 v4, v3, v16
	ds_write2_b32 v43, v2, v4 offset0:24 offset1:28
	v_bfe_u32 v2, v4, 16, 1
	v_add3_u32 v2, v4, v2, s72
	ds_write_b16_d16_hi v5, v2 offset:56
	v_mul_f32_e32 v2, v3, v18
	v_bfe_u32 v4, v2, 16, 1
	v_add3_u32 v4, v2, v4, s72
	ds_write_b16_d16_hi v5, v4 offset:64
	v_mul_f32_e32 v4, v3, v24
	ds_write2_b32 v43, v2, v4 offset0:32 offset1:36
	v_bfe_u32 v2, v4, 16, 1
	v_add3_u32 v2, v4, v2, s72
	ds_write_b16_d16_hi v5, v2 offset:72
	v_mul_f32_e32 v2, v3, v26
	v_bfe_u32 v4, v2, 16, 1
	v_add3_u32 v4, v2, v4, s72
	ds_write_b16_d16_hi v5, v4 offset:80
	v_mul_f32_e32 v4, v3, v28
	ds_write2_b32 v43, v2, v4 offset0:40 offset1:44
	v_bfe_u32 v2, v4, 16, 1
	v_add3_u32 v2, v4, v2, s72
	ds_write_b16_d16_hi v5, v2 offset:88
	v_mul_f32_e32 v2, v3, v30
	v_bfe_u32 v4, v2, 16, 1
	v_add3_u32 v4, v2, v4, s72
	ds_write_b16_d16_hi v5, v4 offset:96
	v_mul_f32_e32 v4, v3, v32
	ds_write2_b32 v43, v2, v4 offset0:48 offset1:52
	v_bfe_u32 v2, v4, 16, 1
	v_add3_u32 v2, v4, v2, s72
	ds_write_b16_d16_hi v5, v2 offset:104
	v_mul_f32_e32 v2, v3, v36
	v_bfe_u32 v4, v2, 16, 1
	v_add3_u32 v4, v2, v4, s72
	ds_write_b16_d16_hi v5, v4 offset:112
	v_mul_f32_e32 v4, v3, v38
	ds_write2_b32 v43, v2, v4 offset0:56 offset1:60
	v_bfe_u32 v2, v4, 16, 1
	v_add3_u32 v2, v4, v2, s72
	ds_write_b16_d16_hi v5, v2 offset:120
	v_mul_f32_e32 v2, v3, v44
	v_bfe_u32 v4, v2, 16, 1
	v_add3_u32 v4, v2, v4, s72
	ds_write_b16_d16_hi v5, v4 offset:128
	v_mul_f32_e32 v4, v3, v46
	ds_write2_b32 v43, v2, v4 offset0:64 offset1:68
	v_bfe_u32 v2, v4, 16, 1
	v_add3_u32 v2, v4, v2, s72
	ds_write_b16_d16_hi v5, v2 offset:136
	v_mul_f32_e32 v2, v3, v48
	v_bfe_u32 v4, v2, 16, 1
	v_add3_u32 v4, v2, v4, s72
	ds_write_b16_d16_hi v5, v4 offset:144
	v_mul_f32_e32 v4, v3, v50
	ds_write2_b32 v43, v2, v4 offset0:72 offset1:76
	v_bfe_u32 v2, v4, 16, 1
	v_add3_u32 v2, v4, v2, s72
	ds_write_b16_d16_hi v5, v2 offset:152
	v_mul_f32_e32 v2, v3, v52
	v_bfe_u32 v4, v2, 16, 1
	v_add3_u32 v4, v2, v4, s72
	ds_write_b16_d16_hi v5, v4 offset:160
	v_mul_f32_e32 v4, v3, v54
	ds_write2_b32 v43, v2, v4 offset0:80 offset1:84
	v_bfe_u32 v2, v4, 16, 1
	v_add3_u32 v2, v4, v2, s72
	ds_write_b16_d16_hi v5, v2 offset:168
	v_mul_f32_e32 v2, v3, v56
	v_bfe_u32 v4, v2, 16, 1
	v_add3_u32 v4, v2, v4, s72
	ds_write_b16_d16_hi v5, v4 offset:176
	v_mul_f32_e32 v4, v3, v58
	ds_write2_b32 v43, v2, v4 offset0:88 offset1:92
	v_bfe_u32 v2, v4, 16, 1
	v_add3_u32 v2, v4, v2, s72
	ds_write_b16_d16_hi v5, v2 offset:184
	v_mul_f32_e32 v2, v3, v60
	v_bfe_u32 v4, v2, 16, 1
	v_add3_u32 v4, v2, v4, s72
	ds_write_b16_d16_hi v5, v4 offset:192
	v_mul_f32_e32 v4, v3, v62
	ds_write2_b32 v43, v2, v4 offset0:96 offset1:100
	v_bfe_u32 v2, v4, 16, 1
	v_add3_u32 v2, v4, v2, s72
	ds_write_b16_d16_hi v5, v2 offset:200
	v_mul_f32_e32 v2, v3, v64
	v_bfe_u32 v4, v2, 16, 1
	v_add3_u32 v4, v2, v4, s72
	ds_write_b16_d16_hi v5, v4 offset:208
	v_mul_f32_e32 v4, v3, v66
	ds_write2_b32 v43, v2, v4 offset0:104 offset1:108
	v_bfe_u32 v2, v4, 16, 1
	v_add3_u32 v2, v4, v2, s72
	ds_write_b16_d16_hi v5, v2 offset:216
	v_mul_f32_e32 v2, v3, v68
	v_bfe_u32 v4, v2, 16, 1
	v_add3_u32 v4, v2, v4, s72
	ds_write_b16_d16_hi v5, v4 offset:224
	v_mul_f32_e32 v4, v3, v70
	ds_write2_b32 v43, v2, v4 offset0:112 offset1:116
	v_bfe_u32 v2, v4, 16, 1
	v_add3_u32 v2, v4, v2, s72
	ds_write_b16_d16_hi v5, v2 offset:232
	ds_read_b32 v2, v43 offset:496
	v_mul_f32_e32 v4, v3, v72
	v_bfe_u32 v6, v4, 16, 1
	v_add3_u32 v6, v4, v6, s72
	ds_write_b16_d16_hi v5, v9
	s_waitcnt lgkmcnt(1)
	v_mul_f32_e32 v2, v3, v2
	v_bfe_u32 v3, v2, 16, 1
	ds_write2_b32 v43, v4, v2 offset0:120 offset1:124
	v_add3_u32 v2, v2, v3, s72
	ds_write_b16_d16_hi v5, v6 offset:240
	ds_write_b16_d16_hi v5, v2 offset:248
	s_and_saveexec_b64 s[0:1], s[40:41]
	s_cbranch_execz .LBB0_376
	v_mov_b32_e32 v2, v42
	s_nop 1
	v_add_f32_dpp v2, v2, v2 row_shr:1 row_mask:0xf bank_mask:0xf bound_ctrl:0
	s_nop 1
	v_add_f32_dpp v2, v2, v2 row_shr:2 row_mask:0xf bank_mask:0xf bound_ctrl:0
	s_nop 1
	v_add_f32_dpp v2, v2, v2 row_shr:4 row_mask:0xf bank_mask:0xf bound_ctrl:0
	s_nop 1
	v_add_f32_dpp v2, v2, v2 row_shr:8 row_mask:0xf bank_mask:0xf bound_ctrl:0
	s_nop 1
	v_add_f32_dpp v2, v2, v2 row_bcast:15 row_mask:0xa bank_mask:0xf
	s_nop 1
	v_add_f32_dpp v2, v2, v2 row_bcast:31 row_mask:0xc bank_mask:0xf
	v_mul_f32_e32 v4, 0x3fb8aa3b, v2
	v_exp_f32_e32 v4, v4
	v_lshl_add_u32 v3, v22, 2, v20
	ds_write_b32 v3, v4 offset:17152
	ds_write2st64_b32 v3, v2, v41 offset0:65 offset1:66
